# same as batched-loads version plus 11 s_nop of dead padding so the attention and GEMM loops keep the baseline 64-byte code alignment
# speedup vs baseline: 1.0068x; 1.0068x over previous
; #define LAS __attribute__((address_space(3)))
; __device__ __forceinline__ void transpose_item(const float* W, int K, int N, const float* g0, const float* g1, bf16_t* WT, LAS unsigned* T, int item, int lane, bool gate_up_interleave = false, bool rope_heads = false) {
;     ...
;     const int c = lane & 7;
; #pragma unroll 4
;     for (int it = 0; it < 16; ++it) {
;         const int n = 8 * it + (lane >> 3);
;         const u32x4 o = *(const LAS u32x4*)(T + n * PD + 4 * c);
;         const int nd = (rope_heads && nb >= 24 && nb < 34) ? ((n < 64) ? (8 * (n >> 2) + (n & 3)) : (8 * ((n - 64) >> 2) + 4 + (n & 3))) : n;
;         *(u32x4*)(WT + (size_t)(dn0 + nd) * K + k0 + 8 * c) = o;
;     }
.LBB0_46:
	s_andn2_b64 vcc, exec, s[4:5]
	s_cbranch_vccnz .LBB0_25
	v_add_u32_e32 v6, 48, v21
	v_and_or_b32 v6, v6, s28, v27
	s_branch .LBB0_25
	s_nop 0
	s_nop 0
	s_nop 0
	s_nop 0
	s_nop 0
	s_nop 0
	s_nop 0
	s_nop 0
	s_nop 0
	s_nop 0
	s_nop 0
